# P2 K-loop: one barrier per 64-deep step, fragment ds_reads of the other half-step overlapped with the MFMAs (software pipelined)
# speedup vs baseline: 1.0089x; 1.0064x over previous
.LBB0_261:
	s_and_b32 s0, s15, 7
	s_cmpk_gt_u32 s34, 0xd7
	s_cselect_b32 s1, 0xffffff28, 0
	s_cselect_b32 s40, 8, 0
	s_and_b32 s13, s34, 7
	v_mov_b32_e32 v149, v178
	s_or_b32 s13, s13, s40
	v_readlane_b32 s41, v235, 6
	s_or_b32 s13, s13, s41
	v_ashrrev_i32_e32 v2, 6, v149
	v_bfe_u32 v12, v149, 3, 3
	v_lshlrev_b32_e32 v13, 5, v2
	s_add_i32 s1, s1, s34
	s_lshl_b32 s13, s13, 7
	v_or_b32_e32 v4, v13, v12
	s_lshl_b32 s1, s1, 4
	v_add_u32_e32 v0, s13, v4
	s_and_b32 s44, s1, 0xffffff80
	v_ashrrev_i32_e32 v1, 31, v0
	v_readlane_b32 s42, v236, 42
	v_lshlrev_b64 v[0:1], 11, v[0:1]
	v_add_u32_e32 v4, s44, v4
	v_bfe_u32 v147, v149, 4, 2
	v_readlane_b32 s43, v236, 43
	v_ashrrev_i32_e32 v5, 31, v4
	v_xor_b32_e32 v6, v147, v149
	v_lshl_add_u64 v[0:1], s[42:43], 0, v[0:1]
	v_readlane_b32 s42, v234, 18
	v_lshlrev_b64 v[4:5], 11, v[4:5]
	v_lshrrev_b32_e32 v7, 4, v149
	v_readlane_b32 s43, v234, 19
	v_lshlrev_b32_e32 v150, 12, v2
	v_lshlrev_b32_e32 v2, 4, v6
	v_bitop3_b32 v10, v7, v149, 4 bitop3:0x36
	v_lshl_add_u64 v[4:5], s[42:43], 0, v[4:5]
	v_and_b32_e32 v2, 0x70, v2
	v_or_b32_e32 v14, 4, v7
	v_add_u32_e32 v151, 0x4000, v150
	v_lshl_add_u64 v[6:7], v[0:1], 0, v[2:3]
	v_readfirstlane_b32 s1, v150
	v_lshl_add_u64 v[8:9], v[4:5], 0, v[2:3]
	v_lshlrev_b32_e32 v2, 4, v10
	s_mov_b32 m0, s1
	v_readfirstlane_b32 s1, v151
	v_and_b32_e32 v2, 0x70, v2
	v_or_b32_e32 v15, 0x400, v150
	global_load_lds_dwordx4 v[6:7], off
	s_mov_b32 m0, s1
	v_lshl_add_u64 v[0:1], v[0:1], 0, v[2:3]
	s_mov_b64 s[42:43], 0x4000
	v_readfirstlane_b32 s1, v15
	v_add_u32_e32 v152, 0x4400, v150
	global_load_lds_dwordx4 v[8:9], off
	v_lshl_add_u64 v[10:11], v[0:1], 0, s[42:43]
	s_mov_b32 m0, s1
	v_lshl_add_u64 v[4:5], v[4:5], 0, v[2:3]
	v_readfirstlane_b32 s1, v152
	v_or_b32_e32 v2, 0x800, v150
	global_load_lds_dwordx4 v[10:11], off
	v_lshl_add_u64 v[10:11], v[4:5], 0, s[42:43]
	s_mov_b32 m0, s1
	s_mov_b64 s[42:43], 0x8000
	v_readfirstlane_b32 s1, v2
	v_add_u32_e32 v153, 0x4800, v150
	global_load_lds_dwordx4 v[10:11], off
	v_lshl_add_u64 v[6:7], v[6:7], 0, s[42:43]
	s_mov_b32 m0, s1
	v_readfirstlane_b32 s1, v153
	v_or_b32_e32 v2, 0xc00, v150
	global_load_lds_dwordx4 v[6:7], off
	v_lshl_add_u64 v[6:7], v[8:9], 0, s[42:43]
	s_mov_b32 m0, s1
	s_mov_b64 s[42:43], 0xc000
	v_readfirstlane_b32 s1, v2
	v_add_u32_e32 v154, 0x4c00, v150
	global_load_lds_dwordx4 v[6:7], off
	v_lshl_add_u64 v[0:1], v[0:1], 0, s[42:43]
	s_mov_b32 m0, s1
	v_readfirstlane_b32 s1, v154
	global_load_lds_dwordx4 v[0:1], off
	v_lshl_add_u64 v[0:1], v[4:5], 0, s[42:43]
	s_mov_b32 m0, s1
	v_ashrrev_i32_e32 v155, 1, v149
	global_load_lds_dwordx4 v[0:1], off
	v_lshrrev_b32_e32 v0, 1, v149
	v_bfe_u32 v1, v149, 1, 3
	v_bitop3_b32 v0, v147, v0, 7 bitop3:0x78
	s_add_i32 s1, s41, s40
	v_and_b32_e32 v146, 15, v149
	v_and_b32_e32 v156, 0xffffffc0, v155
	v_lshlrev_b32_e32 v10, 4, v0
	v_bitop3_b32 v0, v147, v1, 4 bitop3:0x36
	s_add_i32 s1, s1, s0
	v_or_b32_e32 v6, s44, v12
	v_or_b32_e32 v2, v156, v146
	v_lshlrev_b32_e32 v11, 4, v0
	v_lshl_or_b32 v0, s1, 7, v12
	v_add_u32_e32 v6, v6, v13
	v_lshlrev_b32_e32 v8, 7, v2
	v_lshlrev_b32_e32 v2, 7, v149
	v_add_u32_e32 v0, v0, v13
	v_ashrrev_i32_e32 v7, 31, v6
	v_readlane_b32 s0, v234, 9
	v_and_b32_e32 v9, 0x2780, v2
	v_ashrrev_i32_e32 v1, 31, v0
	v_bitop3_b32 v2, v147, 7, v149 bitop3:0x48
	v_bitop3_b32 v4, v14, 7, v149 bitop3:0x48
	v_lshlrev_b64 v[6:7], 11, v[6:7]
	v_readlane_b32 s1, v234, 10
	v_lshlrev_b64 v[0:1], 11, v[0:1]
	v_lshlrev_b32_e32 v2, 4, v2
	v_lshlrev_b32_e32 v4, 4, v4
	v_mov_b32_e32 v5, v3
	v_lshl_add_u64 v[6:7], s[0:1], 0, v[6:7]
	v_mov_b32_e32 v52, 0
	s_mov_b32 s12, 0
	v_and_b32_e32 v148, 63, v149
	v_or_b32_e32 v132, v0, v2
	v_mov_b32_e32 v133, v1
	v_or_b32_e32 v0, v0, v4
	v_lshl_add_u64 v[134:135], v[6:7], 0, v[2:3]
	v_lshl_add_u64 v[136:137], v[6:7], 0, v[4:5]
	v_add_u32_e32 v2, v8, v10
	v_add_u32_e32 v157, v9, v10
	v_add_u32_e32 v158, v8, v11
	v_add_u32_e32 v159, v9, v11
	v_add_u32_e32 v160, 0x8000, v150
	v_add_u32_e32 v161, 0xc000, v150
	v_add_u32_e32 v162, 0x8400, v150
	v_add_u32_e32 v163, 0xc400, v150
	v_add_u32_e32 v164, 0x8800, v150
	v_add_u32_e32 v165, 0xc800, v150
	v_add_u32_e32 v166, 0x8c00, v150
	v_add_u32_e32 v167, 0xcc00, v150
	s_mov_b64 s[0:1], s[24:25]
	v_mov_b32_e32 v53, v52
	v_mov_b32_e32 v54, v52
	v_mov_b32_e32 v55, v52
	v_mov_b32_e32 v64, v52
	v_mov_b32_e32 v65, v52
	v_mov_b32_e32 v66, v52
	v_mov_b32_e32 v67, v52
	v_mov_b32_e32 v60, v52
	v_mov_b32_e32 v61, v52
	v_mov_b32_e32 v62, v52
	v_mov_b32_e32 v63, v52
	v_mov_b32_e32 v56, v52
	v_mov_b32_e32 v57, v52
	v_mov_b32_e32 v58, v52
	v_mov_b32_e32 v59, v52
	v_mov_b32_e32 v48, v52
	v_mov_b32_e32 v49, v52
	v_mov_b32_e32 v50, v52
	v_mov_b32_e32 v51, v52
	v_mov_b32_e32 v44, v52
	v_mov_b32_e32 v45, v52
	v_mov_b32_e32 v46, v52
	v_mov_b32_e32 v47, v52
	v_mov_b32_e32 v40, v52
	v_mov_b32_e32 v41, v52
	v_mov_b32_e32 v42, v52
	v_mov_b32_e32 v43, v52
	v_mov_b32_e32 v36, v52
	v_mov_b32_e32 v37, v52
	v_mov_b32_e32 v38, v52
	v_mov_b32_e32 v39, v52
	v_mov_b32_e32 v32, v52
	v_mov_b32_e32 v33, v52
	v_mov_b32_e32 v34, v52
	v_mov_b32_e32 v35, v52
	v_mov_b32_e32 v28, v52
	v_mov_b32_e32 v29, v52
	v_mov_b32_e32 v30, v52
	v_mov_b32_e32 v31, v52
	v_mov_b32_e32 v24, v52
	v_mov_b32_e32 v25, v52
	v_mov_b32_e32 v26, v52
	v_mov_b32_e32 v27, v52
	v_mov_b32_e32 v20, v52
	v_mov_b32_e32 v21, v52
	v_mov_b32_e32 v22, v52
	v_mov_b32_e32 v23, v52
	v_mov_b32_e32 v16, v52
	v_mov_b32_e32 v17, v52
	v_mov_b32_e32 v18, v52
	v_mov_b32_e32 v19, v52
	v_mov_b32_e32 v12, v52
	v_mov_b32_e32 v13, v52
	v_mov_b32_e32 v14, v52
	v_mov_b32_e32 v15, v52
	v_mov_b32_e32 v8, v52
	v_mov_b32_e32 v9, v52
	v_mov_b32_e32 v10, v52
	v_mov_b32_e32 v11, v52
	v_mov_b32_e32 v4, v52
	v_mov_b32_e32 v5, v52
	v_mov_b32_e32 v6, v52
	v_mov_b32_e32 v7, v52
	v_add_u32_e32 v172, 0x4000, v0
	v_add_u32_e32 v173, 0x8000, v132
	v_add_u32_e32 v174, 0xc000, v0
	v_add_u32_e32 v175, 0x4000, v136
	v_add_u32_e32 v176, 0x8000, v134
	v_add_u32_e32 v177, 0xc000, v136
	v_readfirstlane_b32 s42, v150
	s_add_u32 s0, s24, 0x4c47080
	s_addc_u32 s1, s25, 0
	s_add_u32 s40, s24, 0x467080
	s_addc_u32 s41, s25, 0
	s_add_u32 m0, s42, 0x8000
	s_nop 0
	global_load_lds_dwordx4 v132, s[0:1]
	s_add_u32 m0, s42, 0xc000
	s_nop 0
	global_load_lds_dwordx4 v134, s[40:41]
	s_add_u32 m0, s42, 0x8400
	s_nop 0
	global_load_lds_dwordx4 v172, s[0:1]
	s_add_u32 m0, s42, 0xc400
	s_nop 0
	global_load_lds_dwordx4 v175, s[40:41]
	s_add_u32 m0, s42, 0x8800
	s_nop 0
	global_load_lds_dwordx4 v173, s[0:1]
	s_add_u32 m0, s42, 0xc800
	s_nop 0
	global_load_lds_dwordx4 v176, s[40:41]
	s_add_u32 m0, s42, 0x8c00
	s_nop 0
	global_load_lds_dwordx4 v174, s[0:1]
	s_add_u32 m0, s42, 0xcc00
	s_nop 0
	global_load_lds_dwordx4 v177, s[40:41]
	s_add_u32 s0, s0, 0x80
	s_addc_u32 s1, s1, 0
	s_add_u32 s40, s40, 0x80
	s_addc_u32 s41, s41, 0
	s_waitcnt vmcnt(8)
	s_barrier
	ds_read_b128 v[76:79], v157 offset:16384
	ds_read_b128 v[68:71], v2 offset:0
	ds_read_b128 v[80:83], v157 offset:18432
	ds_read_b128 v[72:75], v2 offset:2048
	ds_read_b128 v[92:95], v157 offset:20480
	ds_read_b128 v[84:87], v2 offset:4096
	ds_read_b128 v[96:99], v157 offset:22528
	ds_read_b128 v[88:91], v2 offset:6144
	s_mov_b32 s12, 0
.Lp2k_loop:
	s_waitcnt lgkmcnt(0)
	v_mfma_f32_16x16x32_bf16 v[52:55], v[76:79], v[68:71], v[52:55]
	ds_read_b128 v[108:111], v159 offset:16384
	ds_read_b128 v[100:103], v158 offset:0
	v_mfma_f32_16x16x32_bf16 v[64:67], v[80:83], v[68:71], v[64:67]
	ds_read_b128 v[112:115], v159 offset:18432
	ds_read_b128 v[104:107], v158 offset:2048
	v_mfma_f32_16x16x32_bf16 v[60:63], v[92:95], v[68:71], v[60:63]
	ds_read_b128 v[124:127], v159 offset:20480
	ds_read_b128 v[116:119], v158 offset:4096
	v_mfma_f32_16x16x32_bf16 v[56:59], v[96:99], v[68:71], v[56:59]
	ds_read_b128 v[128:131], v159 offset:22528
	ds_read_b128 v[120:123], v158 offset:6144
	v_mfma_f32_16x16x32_bf16 v[48:51], v[76:79], v[72:75], v[48:51]
	v_mfma_f32_16x16x32_bf16 v[44:47], v[80:83], v[72:75], v[44:47]
	v_mfma_f32_16x16x32_bf16 v[40:43], v[92:95], v[72:75], v[40:43]
	v_mfma_f32_16x16x32_bf16 v[36:39], v[96:99], v[72:75], v[36:39]
	v_mfma_f32_16x16x32_bf16 v[32:35], v[76:79], v[84:87], v[32:35]
	v_mfma_f32_16x16x32_bf16 v[28:31], v[80:83], v[84:87], v[28:31]
	v_mfma_f32_16x16x32_bf16 v[24:27], v[92:95], v[84:87], v[24:27]
	v_mfma_f32_16x16x32_bf16 v[20:23], v[96:99], v[84:87], v[20:23]
	v_mfma_f32_16x16x32_bf16 v[16:19], v[76:79], v[88:91], v[16:19]
	v_mfma_f32_16x16x32_bf16 v[12:15], v[80:83], v[88:91], v[12:15]
	v_mfma_f32_16x16x32_bf16 v[8:11], v[92:95], v[88:91], v[8:11]
	v_mfma_f32_16x16x32_bf16 v[4:7], v[96:99], v[88:91], v[4:7]
	s_waitcnt lgkmcnt(0)
	s_waitcnt vmcnt(0)
	s_barrier
	s_add_u32 m0, s42, 0x0
	v_mfma_f32_16x16x32_bf16 v[52:55], v[108:111], v[100:103], v[52:55]
	global_load_lds_dwordx4 v132, s[0:1]
	ds_read_b128 v[76:79], v157 offset:49152
	ds_read_b128 v[68:71], v2 offset:32768
	v_mfma_f32_16x16x32_bf16 v[64:67], v[112:115], v[100:103], v[64:67]
	ds_read_b128 v[80:83], v157 offset:51200
	ds_read_b128 v[72:75], v2 offset:34816
	s_add_u32 m0, s42, 0x4000
	v_mfma_f32_16x16x32_bf16 v[60:63], v[124:127], v[100:103], v[60:63]
	global_load_lds_dwordx4 v134, s[40:41]
	ds_read_b128 v[92:95], v157 offset:53248
	ds_read_b128 v[84:87], v2 offset:36864
	v_mfma_f32_16x16x32_bf16 v[56:59], v[128:131], v[100:103], v[56:59]
	ds_read_b128 v[96:99], v157 offset:55296
	ds_read_b128 v[88:91], v2 offset:38912
	s_add_u32 m0, s42, 0x400
	v_mfma_f32_16x16x32_bf16 v[48:51], v[108:111], v[104:107], v[48:51]
	global_load_lds_dwordx4 v172, s[0:1]
	v_mfma_f32_16x16x32_bf16 v[44:47], v[112:115], v[104:107], v[44:47]
	s_add_u32 m0, s42, 0x4400
	v_mfma_f32_16x16x32_bf16 v[40:43], v[124:127], v[104:107], v[40:43]
	global_load_lds_dwordx4 v175, s[40:41]
	v_mfma_f32_16x16x32_bf16 v[36:39], v[128:131], v[104:107], v[36:39]
	s_add_u32 m0, s42, 0x800
	v_mfma_f32_16x16x32_bf16 v[32:35], v[108:111], v[116:119], v[32:35]
	global_load_lds_dwordx4 v173, s[0:1]
	v_mfma_f32_16x16x32_bf16 v[28:31], v[112:115], v[116:119], v[28:31]
	s_add_u32 m0, s42, 0x4800
	v_mfma_f32_16x16x32_bf16 v[24:27], v[124:127], v[116:119], v[24:27]
	global_load_lds_dwordx4 v176, s[40:41]
	v_mfma_f32_16x16x32_bf16 v[20:23], v[128:131], v[116:119], v[20:23]
	s_add_u32 m0, s42, 0xc00
	v_mfma_f32_16x16x32_bf16 v[16:19], v[108:111], v[120:123], v[16:19]
	global_load_lds_dwordx4 v174, s[0:1]
	v_mfma_f32_16x16x32_bf16 v[12:15], v[112:115], v[120:123], v[12:15]
	s_add_u32 m0, s42, 0x4c00
	v_mfma_f32_16x16x32_bf16 v[8:11], v[124:127], v[120:123], v[8:11]
	global_load_lds_dwordx4 v177, s[40:41]
	v_mfma_f32_16x16x32_bf16 v[4:7], v[128:131], v[120:123], v[4:7]
	s_add_u32 s0, s0, 0x80
	s_addc_u32 s1, s1, 0
	s_add_u32 s40, s40, 0x80
	s_addc_u32 s41, s41, 0
	s_waitcnt lgkmcnt(0)
	v_mfma_f32_16x16x32_bf16 v[52:55], v[76:79], v[68:71], v[52:55]
	ds_read_b128 v[108:111], v159 offset:49152
	ds_read_b128 v[100:103], v158 offset:32768
	v_mfma_f32_16x16x32_bf16 v[64:67], v[80:83], v[68:71], v[64:67]
	ds_read_b128 v[112:115], v159 offset:51200
	ds_read_b128 v[104:107], v158 offset:34816
	v_mfma_f32_16x16x32_bf16 v[60:63], v[92:95], v[68:71], v[60:63]
	ds_read_b128 v[124:127], v159 offset:53248
	ds_read_b128 v[116:119], v158 offset:36864
	v_mfma_f32_16x16x32_bf16 v[56:59], v[96:99], v[68:71], v[56:59]
	ds_read_b128 v[128:131], v159 offset:55296
	ds_read_b128 v[120:123], v158 offset:38912
	v_mfma_f32_16x16x32_bf16 v[48:51], v[76:79], v[72:75], v[48:51]
	v_mfma_f32_16x16x32_bf16 v[44:47], v[80:83], v[72:75], v[44:47]
	v_mfma_f32_16x16x32_bf16 v[40:43], v[92:95], v[72:75], v[40:43]
	v_mfma_f32_16x16x32_bf16 v[36:39], v[96:99], v[72:75], v[36:39]
	v_mfma_f32_16x16x32_bf16 v[32:35], v[76:79], v[84:87], v[32:35]
	v_mfma_f32_16x16x32_bf16 v[28:31], v[80:83], v[84:87], v[28:31]
	v_mfma_f32_16x16x32_bf16 v[24:27], v[92:95], v[84:87], v[24:27]
	v_mfma_f32_16x16x32_bf16 v[20:23], v[96:99], v[84:87], v[20:23]
	v_mfma_f32_16x16x32_bf16 v[16:19], v[76:79], v[88:91], v[16:19]
	v_mfma_f32_16x16x32_bf16 v[12:15], v[80:83], v[88:91], v[12:15]
	v_mfma_f32_16x16x32_bf16 v[8:11], v[92:95], v[88:91], v[8:11]
	v_mfma_f32_16x16x32_bf16 v[4:7], v[96:99], v[88:91], v[4:7]
	s_waitcnt lgkmcnt(0)
	s_waitcnt vmcnt(0)
	s_barrier
	s_add_u32 m0, s42, 0x8000
	v_mfma_f32_16x16x32_bf16 v[52:55], v[108:111], v[100:103], v[52:55]
	global_load_lds_dwordx4 v132, s[0:1]
	ds_read_b128 v[76:79], v157 offset:16384
	ds_read_b128 v[68:71], v2 offset:0
	v_mfma_f32_16x16x32_bf16 v[64:67], v[112:115], v[100:103], v[64:67]
	ds_read_b128 v[80:83], v157 offset:18432
	ds_read_b128 v[72:75], v2 offset:2048
	s_add_u32 m0, s42, 0xc000
	v_mfma_f32_16x16x32_bf16 v[60:63], v[124:127], v[100:103], v[60:63]
	global_load_lds_dwordx4 v134, s[40:41]
	ds_read_b128 v[92:95], v157 offset:20480
	ds_read_b128 v[84:87], v2 offset:4096
	v_mfma_f32_16x16x32_bf16 v[56:59], v[128:131], v[100:103], v[56:59]
	ds_read_b128 v[96:99], v157 offset:22528
	ds_read_b128 v[88:91], v2 offset:6144
	s_add_u32 m0, s42, 0x8400
	v_mfma_f32_16x16x32_bf16 v[48:51], v[108:111], v[104:107], v[48:51]
	global_load_lds_dwordx4 v172, s[0:1]
	v_mfma_f32_16x16x32_bf16 v[44:47], v[112:115], v[104:107], v[44:47]
	s_add_u32 m0, s42, 0xc400
	v_mfma_f32_16x16x32_bf16 v[40:43], v[124:127], v[104:107], v[40:43]
	global_load_lds_dwordx4 v175, s[40:41]
	v_mfma_f32_16x16x32_bf16 v[36:39], v[128:131], v[104:107], v[36:39]
	s_add_u32 m0, s42, 0x8800
	v_mfma_f32_16x16x32_bf16 v[32:35], v[108:111], v[116:119], v[32:35]
	global_load_lds_dwordx4 v173, s[0:1]
	v_mfma_f32_16x16x32_bf16 v[28:31], v[112:115], v[116:119], v[28:31]
	s_add_u32 m0, s42, 0xc800
	v_mfma_f32_16x16x32_bf16 v[24:27], v[124:127], v[116:119], v[24:27]
	global_load_lds_dwordx4 v176, s[40:41]
	v_mfma_f32_16x16x32_bf16 v[20:23], v[128:131], v[116:119], v[20:23]
	s_add_u32 m0, s42, 0x8c00
	v_mfma_f32_16x16x32_bf16 v[16:19], v[108:111], v[120:123], v[16:19]
	global_load_lds_dwordx4 v174, s[0:1]
	v_mfma_f32_16x16x32_bf16 v[12:15], v[112:115], v[120:123], v[12:15]
	s_add_u32 m0, s42, 0xcc00
	v_mfma_f32_16x16x32_bf16 v[8:11], v[124:127], v[120:123], v[8:11]
	global_load_lds_dwordx4 v177, s[40:41]
	v_mfma_f32_16x16x32_bf16 v[4:7], v[128:131], v[120:123], v[4:7]
	s_add_u32 s0, s0, 0x80
	s_addc_u32 s1, s1, 0
	s_add_u32 s40, s40, 0x80
	s_addc_u32 s41, s41, 0
	s_add_u32 s12, s12, 1
	s_cmp_lt_u32 s12, 7
	s_cbranch_scc1 .Lp2k_loop
	s_waitcnt lgkmcnt(0)
	v_mfma_f32_16x16x32_bf16 v[52:55], v[76:79], v[68:71], v[52:55]
	ds_read_b128 v[108:111], v159 offset:16384
	ds_read_b128 v[100:103], v158 offset:0
	v_mfma_f32_16x16x32_bf16 v[64:67], v[80:83], v[68:71], v[64:67]
	ds_read_b128 v[112:115], v159 offset:18432
	ds_read_b128 v[104:107], v158 offset:2048
	v_mfma_f32_16x16x32_bf16 v[60:63], v[92:95], v[68:71], v[60:63]
	ds_read_b128 v[124:127], v159 offset:20480
	ds_read_b128 v[116:119], v158 offset:4096
	v_mfma_f32_16x16x32_bf16 v[56:59], v[96:99], v[68:71], v[56:59]
	ds_read_b128 v[128:131], v159 offset:22528
	ds_read_b128 v[120:123], v158 offset:6144
	v_mfma_f32_16x16x32_bf16 v[48:51], v[76:79], v[72:75], v[48:51]
	v_mfma_f32_16x16x32_bf16 v[44:47], v[80:83], v[72:75], v[44:47]
	v_mfma_f32_16x16x32_bf16 v[40:43], v[92:95], v[72:75], v[40:43]
	v_mfma_f32_16x16x32_bf16 v[36:39], v[96:99], v[72:75], v[36:39]
	v_mfma_f32_16x16x32_bf16 v[32:35], v[76:79], v[84:87], v[32:35]
	v_mfma_f32_16x16x32_bf16 v[28:31], v[80:83], v[84:87], v[28:31]
	v_mfma_f32_16x16x32_bf16 v[24:27], v[92:95], v[84:87], v[24:27]
	v_mfma_f32_16x16x32_bf16 v[20:23], v[96:99], v[84:87], v[20:23]
	v_mfma_f32_16x16x32_bf16 v[16:19], v[76:79], v[88:91], v[16:19]
	v_mfma_f32_16x16x32_bf16 v[12:15], v[80:83], v[88:91], v[12:15]
	v_mfma_f32_16x16x32_bf16 v[8:11], v[92:95], v[88:91], v[8:11]
	v_mfma_f32_16x16x32_bf16 v[4:7], v[96:99], v[88:91], v[4:7]
	s_waitcnt lgkmcnt(0)
	s_waitcnt vmcnt(0)
	s_barrier
	v_mfma_f32_16x16x32_bf16 v[52:55], v[108:111], v[100:103], v[52:55]
	ds_read_b128 v[76:79], v157 offset:49152
	ds_read_b128 v[68:71], v2 offset:32768
	v_mfma_f32_16x16x32_bf16 v[64:67], v[112:115], v[100:103], v[64:67]
	ds_read_b128 v[80:83], v157 offset:51200
	ds_read_b128 v[72:75], v2 offset:34816
	v_mfma_f32_16x16x32_bf16 v[60:63], v[124:127], v[100:103], v[60:63]
	ds_read_b128 v[92:95], v157 offset:53248
	ds_read_b128 v[84:87], v2 offset:36864
	v_mfma_f32_16x16x32_bf16 v[56:59], v[128:131], v[100:103], v[56:59]
	ds_read_b128 v[96:99], v157 offset:55296
	ds_read_b128 v[88:91], v2 offset:38912
	v_mfma_f32_16x16x32_bf16 v[48:51], v[108:111], v[104:107], v[48:51]
	v_mfma_f32_16x16x32_bf16 v[44:47], v[112:115], v[104:107], v[44:47]
	v_mfma_f32_16x16x32_bf16 v[40:43], v[124:127], v[104:107], v[40:43]
	v_mfma_f32_16x16x32_bf16 v[36:39], v[128:131], v[104:107], v[36:39]
	v_mfma_f32_16x16x32_bf16 v[32:35], v[108:111], v[116:119], v[32:35]
	v_mfma_f32_16x16x32_bf16 v[28:31], v[112:115], v[116:119], v[28:31]
	v_mfma_f32_16x16x32_bf16 v[24:27], v[124:127], v[116:119], v[24:27]
	v_mfma_f32_16x16x32_bf16 v[20:23], v[128:131], v[116:119], v[20:23]
	v_mfma_f32_16x16x32_bf16 v[16:19], v[108:111], v[120:123], v[16:19]
	v_mfma_f32_16x16x32_bf16 v[12:15], v[112:115], v[120:123], v[12:15]
	v_mfma_f32_16x16x32_bf16 v[8:11], v[124:127], v[120:123], v[8:11]
	v_mfma_f32_16x16x32_bf16 v[4:7], v[128:131], v[120:123], v[4:7]
	s_waitcnt lgkmcnt(0)
	v_mfma_f32_16x16x32_bf16 v[52:55], v[76:79], v[68:71], v[52:55]
	ds_read_b128 v[108:111], v159 offset:49152
	ds_read_b128 v[100:103], v158 offset:32768
	v_mfma_f32_16x16x32_bf16 v[64:67], v[80:83], v[68:71], v[64:67]
	ds_read_b128 v[112:115], v159 offset:51200
	ds_read_b128 v[104:107], v158 offset:34816
	v_mfma_f32_16x16x32_bf16 v[60:63], v[92:95], v[68:71], v[60:63]
	ds_read_b128 v[124:127], v159 offset:53248
	ds_read_b128 v[116:119], v158 offset:36864
	v_mfma_f32_16x16x32_bf16 v[56:59], v[96:99], v[68:71], v[56:59]
	ds_read_b128 v[128:131], v159 offset:55296
	ds_read_b128 v[120:123], v158 offset:38912
	v_mfma_f32_16x16x32_bf16 v[48:51], v[76:79], v[72:75], v[48:51]
	v_mfma_f32_16x16x32_bf16 v[44:47], v[80:83], v[72:75], v[44:47]
	v_mfma_f32_16x16x32_bf16 v[40:43], v[92:95], v[72:75], v[40:43]
	v_mfma_f32_16x16x32_bf16 v[36:39], v[96:99], v[72:75], v[36:39]
	v_mfma_f32_16x16x32_bf16 v[32:35], v[76:79], v[84:87], v[32:35]
	v_mfma_f32_16x16x32_bf16 v[28:31], v[80:83], v[84:87], v[28:31]
	v_mfma_f32_16x16x32_bf16 v[24:27], v[92:95], v[84:87], v[24:27]
	v_mfma_f32_16x16x32_bf16 v[20:23], v[96:99], v[84:87], v[20:23]
	v_mfma_f32_16x16x32_bf16 v[16:19], v[76:79], v[88:91], v[16:19]
	v_mfma_f32_16x16x32_bf16 v[12:15], v[80:83], v[88:91], v[12:15]
	v_mfma_f32_16x16x32_bf16 v[8:11], v[92:95], v[88:91], v[8:11]
	v_mfma_f32_16x16x32_bf16 v[4:7], v[96:99], v[88:91], v[4:7]
	s_waitcnt lgkmcnt(0)
	v_mfma_f32_16x16x32_bf16 v[52:55], v[108:111], v[100:103], v[52:55]
	v_mfma_f32_16x16x32_bf16 v[64:67], v[112:115], v[100:103], v[64:67]
	v_mfma_f32_16x16x32_bf16 v[60:63], v[124:127], v[100:103], v[60:63]
	v_mfma_f32_16x16x32_bf16 v[56:59], v[128:131], v[100:103], v[56:59]
	v_mfma_f32_16x16x32_bf16 v[48:51], v[108:111], v[104:107], v[48:51]
	v_mfma_f32_16x16x32_bf16 v[44:47], v[112:115], v[104:107], v[44:47]
	v_mfma_f32_16x16x32_bf16 v[40:43], v[124:127], v[104:107], v[40:43]
	v_mfma_f32_16x16x32_bf16 v[36:39], v[128:131], v[104:107], v[36:39]
	v_mfma_f32_16x16x32_bf16 v[32:35], v[108:111], v[116:119], v[32:35]
	v_mfma_f32_16x16x32_bf16 v[28:31], v[112:115], v[116:119], v[28:31]
	v_mfma_f32_16x16x32_bf16 v[24:27], v[124:127], v[116:119], v[24:27]
	v_mfma_f32_16x16x32_bf16 v[20:23], v[128:131], v[116:119], v[20:23]
	v_mfma_f32_16x16x32_bf16 v[16:19], v[108:111], v[120:123], v[16:19]
	v_mfma_f32_16x16x32_bf16 v[12:15], v[112:115], v[120:123], v[12:15]
	v_mfma_f32_16x16x32_bf16 v[8:11], v[124:127], v[120:123], v[8:11]
	v_mfma_f32_16x16x32_bf16 v[4:7], v[128:131], v[120:123], v[4:7]
	s_barrier
	s_branch .LBB0_265
